# v68 + P0 RMSNorm store part: f32->bf16 RNE via v_cvt_pk_bf16_f32 instead of the 7-instruction bit trick per pair
# speedup vs baseline: 1.0039x; 1.0039x over previous
.LBB0_49:
	s_or_b64 exec, exec, s[4:5]
	v_mov_b64_e32 v[92:93], v[120:121]
	v_mov_b64_e32 v[94:95], v[122:123]
	v_div_scale_f32 v96, s[4:5], v66, v66, 1.0
	v_div_scale_f32 v98, s[4:5], v82, v82, 1.0
	v_rcp_f32_e32 v104, v96
	v_div_scale_f32 v100, s[6:7], v84, v84, 1.0
	v_rcp_f32_e32 v105, v98
	v_div_scale_f32 v102, s[8:9], v86, v86, 1.0
	v_rcp_f32_e32 v106, v100
	v_rcp_f32_e32 v107, v102
	v_fma_f32 v108, -v96, v104, 1.0
	v_div_scale_f32 v97, vcc, 1.0, v66, 1.0
	v_fma_f32 v109, -v98, v105, 1.0
	v_fmac_f32_e32 v104, v108, v104
	v_div_scale_f32 v99, s[4:5], 1.0, v82, 1.0
	v_fma_f32 v110, -v100, v106, 1.0
	v_fmac_f32_e32 v105, v109, v105
	v_mul_f32_e32 v108, v97, v104
	v_div_scale_f32 v101, s[6:7], 1.0, v84, 1.0
	v_fma_f32 v111, -v102, v107, 1.0
	v_fmac_f32_e32 v106, v110, v106
	v_mul_f32_e32 v109, v99, v105
	v_fma_f32 v112, -v96, v108, v97
	v_div_scale_f32 v103, s[8:9], 1.0, v86, 1.0
	v_fmac_f32_e32 v107, v111, v107
	v_mul_f32_e32 v110, v101, v106
	v_fma_f32 v113, -v98, v109, v99
	v_fmac_f32_e32 v108, v112, v104
	v_mul_f32_e32 v111, v103, v107
	v_fma_f32 v114, -v100, v110, v101
	v_fmac_f32_e32 v109, v113, v105
	v_fma_f32 v96, -v96, v108, v97
	v_fma_f32 v115, -v102, v111, v103
	v_fmac_f32_e32 v110, v114, v106
	v_fma_f32 v97, -v98, v109, v99
	v_div_fmas_f32 v96, v96, v104, v108
	s_mov_b64 vcc, s[4:5]
	v_fmac_f32_e32 v111, v115, v107
	v_fma_f32 v98, -v100, v110, v101
	v_div_fixup_f32 v66, v96, v66, 1.0
	v_div_fmas_f32 v96, v97, v105, v109
	s_mov_b64 vcc, s[6:7]
	v_fma_f32 v99, -v102, v111, v103
	v_div_fixup_f32 v82, v96, v82, 1.0
	v_div_fmas_f32 v96, v98, v106, v110
	s_mov_b64 vcc, s[8:9]
	v_div_fixup_f32 v84, v96, v84, 1.0
	v_div_fmas_f32 v96, v99, v107, v111
	v_div_fixup_f32 v86, v96, v86, 1.0
	v_pk_mul_f32 v[58:59], v[58:59], v[86:87] op_sel_hi:[1,0]
	v_pk_mul_f32 v[60:61], v[60:61], v[86:87] op_sel_hi:[1,0]
	v_lshl_add_u64 v[80:81], s[52:53], 0, v[72:73]
	v_pk_mul_f32 v[62:63], v[62:63], v[84:85] op_sel_hi:[1,0]
	v_add_co_u32_e64 v80, s[10:11], s63, v80
	v_pk_mul_f32 v[64:65], v[64:65], v[84:85] op_sel_hi:[1,0]
	s_nop 0
	v_addc_co_u32_e64 v81, s[10:11], 0, v81, s[10:11]
	v_pk_mul_f32 v[54:55], v[54:55], v[82:83] op_sel_hi:[1,0]
	v_pk_mul_f32 v[56:57], v[56:57], v[82:83] op_sel_hi:[1,0]
	v_pk_mul_f32 v[50:51], v[50:51], v[66:67] op_sel_hi:[1,0]
	v_pk_mul_f32 v[52:53], v[52:53], v[66:67] op_sel_hi:[1,0]
	v_pk_mul_f32 v[38:39], v[38:39], v[86:87] op_sel_hi:[1,0]
	v_pk_mul_f32 v[40:41], v[40:41], v[86:87] op_sel_hi:[1,0]
	v_pk_mul_f32 v[42:43], v[42:43], v[84:85] op_sel_hi:[1,0]
	v_pk_mul_f32 v[44:45], v[44:45], v[84:85] op_sel_hi:[1,0]
	v_pk_mul_f32 v[46:47], v[46:47], v[82:83] op_sel_hi:[1,0]
	v_pk_mul_f32 v[48:49], v[48:49], v[82:83] op_sel_hi:[1,0]
	v_pk_mul_f32 v[34:35], v[34:35], v[66:67] op_sel_hi:[1,0]
	v_pk_mul_f32 v[36:37], v[36:37], v[66:67] op_sel_hi:[1,0]
	v_pk_mul_f32 v[18:19], v[18:19], v[86:87] op_sel_hi:[1,0]
	v_pk_mul_f32 v[20:21], v[20:21], v[86:87] op_sel_hi:[1,0]
	v_pk_mul_f32 v[30:31], v[30:31], v[66:67] op_sel_hi:[1,0]
	v_pk_mul_f32 v[60:61], v[60:61], v[94:95]
	v_pk_mul_f32 v[58:59], v[58:59], v[92:93]
	v_pk_mul_f32 v[62:63], v[62:63], v[92:93]
	v_cvt_pk_bf16_f32 v58, v58, v59
	v_cvt_pk_bf16_f32 v59, v60, v61
	global_store_dwordx2 v[80:81], v[58:59], off
	v_pk_mul_f32 v[64:65], v[64:65], v[94:95]
	v_cvt_pk_bf16_f32 v60, v62, v63
	v_cvt_pk_bf16_f32 v61, v64, v65
	v_lshl_add_u64 v[58:59], s[52:53], 0, v[74:75]
	v_pk_mul_f32 v[54:55], v[54:55], v[92:93]
	global_store_dwordx2 v[58:59], v[60:61], off offset:-1024
	v_pk_mul_f32 v[56:57], v[56:57], v[94:95]
	v_cvt_pk_bf16_f32 v60, v54, v55
	v_pk_mul_f32 v[50:51], v[50:51], v[92:93]
	v_pk_mul_f32 v[52:53], v[52:53], v[94:95]
	v_cvt_pk_bf16_f32 v61, v56, v57
	v_cvt_pk_bf16_f32 v56, v50, v51
	v_lshl_add_u64 v[54:55], s[52:53], 0, v[76:77]
	v_cvt_pk_bf16_f32 v57, v52, v53
	v_lshl_add_u64 v[50:51], s[52:53], 0, v[78:79]
	global_store_dwordx2 v[54:55], v[60:61], off offset:-1024
	global_store_dwordx2 v[50:51], v[56:57], off offset:-1024
	s_nop 1
	v_mov_b64_e32 v[60:61], v[124:125]
	v_mov_b64_e32 v[62:63], v[126:127]
	v_pk_mul_f32 v[32:33], v[32:33], v[66:67] op_sel_hi:[1,0]
	v_pk_mul_f32 v[26:27], v[26:27], v[82:83] op_sel_hi:[1,0]
	v_pk_mul_f32 v[28:29], v[28:29], v[82:83] op_sel_hi:[1,0]
	v_pk_mul_f32 v[22:23], v[22:23], v[84:85] op_sel_hi:[1,0]
	v_pk_mul_f32 v[24:25], v[24:25], v[84:85] op_sel_hi:[1,0]
	s_add_i32 s12, s12, s18
	s_add_u32 s46, s46, s28
	s_addc_u32 s47, s47, s29
	s_add_u32 s48, s48, s28
	v_pk_mul_f32 v[2:3], v[2:3], v[86:87] op_sel_hi:[1,0]
	v_pk_mul_f32 v[4:5], v[4:5], v[86:87] op_sel_hi:[1,0]
	s_addc_u32 s49, s49, s29
	v_pk_mul_f32 v[14:15], v[14:15], v[66:67] op_sel_hi:[1,0]
	v_pk_mul_f32 v[16:17], v[16:17], v[66:67] op_sel_hi:[1,0]
	v_pk_mul_f32 v[10:11], v[10:11], v[82:83] op_sel_hi:[1,0]
	v_pk_mul_f32 v[12:13], v[12:13], v[82:83] op_sel_hi:[1,0]
	v_pk_mul_f32 v[6:7], v[6:7], v[84:85] op_sel_hi:[1,0]
	v_pk_mul_f32 v[8:9], v[8:9], v[84:85] op_sel_hi:[1,0]
	s_add_u32 s56, s56, s28
	s_addc_u32 s57, s57, s29
	s_add_u32 s60, s60, s28
	s_addc_u32 s61, s61, s29
	v_lshl_add_u64 v[70:71], v[70:71], 0, s[36:37]
	v_lshl_add_u64 v[72:73], v[72:73], 0, s[44:45]
	v_lshl_add_u64 v[74:75], v[74:75], 0, s[44:45]
	v_lshl_add_u64 v[76:77], v[76:77], 0, s[44:45]
	s_cmpk_gt_i32 s12, 0x3fff
	v_lshl_add_u64 v[78:79], v[78:79], 0, s[44:45]
	v_pk_mul_f32 v[40:41], v[40:41], v[62:63]
	v_pk_mul_f32 v[38:39], v[38:39], v[60:61]
	v_pk_mul_f32 v[44:45], v[44:45], v[62:63]
	v_pk_mul_f32 v[42:43], v[42:43], v[60:61]
	v_pk_mul_f32 v[46:47], v[46:47], v[60:61]
	v_cvt_pk_bf16_f32 v38, v38, v39
	v_cvt_pk_bf16_f32 v39, v40, v41
	v_cvt_pk_bf16_f32 v40, v42, v43
	v_cvt_pk_bf16_f32 v41, v44, v45
	global_store_dwordx2 v[80:81], v[38:39], off offset:512
	global_store_dwordx2 v[58:59], v[40:41], off offset:-512
	v_pk_mul_f32 v[48:49], v[48:49], v[62:63]
	v_cvt_pk_bf16_f32 v38, v46, v47
	v_cvt_pk_bf16_f32 v39, v48, v49
	v_pk_mul_f32 v[34:35], v[34:35], v[60:61]
	global_store_dwordx2 v[54:55], v[38:39], off offset:-512
	v_pk_mul_f32 v[36:37], v[36:37], v[62:63]
	v_cvt_pk_bf16_f32 v34, v34, v35
	v_cvt_pk_bf16_f32 v35, v36, v37
	global_store_dwordx2 v[50:51], v[34:35], off offset:-512
	s_nop 1
	v_mov_b64_e32 v[34:35], v[128:129]
	v_mov_b64_e32 v[36:37], v[130:131]
	v_pk_mul_f32 v[20:21], v[20:21], v[36:37]
	v_pk_mul_f32 v[18:19], v[18:19], v[34:35]
	v_pk_mul_f32 v[24:25], v[24:25], v[36:37]
	v_pk_mul_f32 v[22:23], v[22:23], v[34:35]
	v_pk_mul_f32 v[28:29], v[28:29], v[36:37]
	v_pk_mul_f32 v[26:27], v[26:27], v[34:35]
	v_pk_mul_f32 v[32:33], v[32:33], v[36:37]
	v_pk_mul_f32 v[30:31], v[30:31], v[34:35]
	v_cvt_pk_bf16_f32 v18, v18, v19
	v_cvt_pk_bf16_f32 v19, v20, v21
	v_cvt_pk_bf16_f32 v20, v22, v23
	v_cvt_pk_bf16_f32 v21, v24, v25
	v_cvt_pk_bf16_f32 v22, v26, v27
	v_cvt_pk_bf16_f32 v23, v28, v29
	global_store_dwordx2 v[80:81], v[18:19], off offset:1024
	global_store_dwordx2 v[58:59], v[20:21], off
	global_store_dwordx2 v[54:55], v[22:23], off
	v_cvt_pk_bf16_f32 v18, v30, v31
	v_cvt_pk_bf16_f32 v19, v32, v33
	global_store_dwordx2 v[50:51], v[18:19], off
	s_nop 1
	v_mov_b64_e32 v[18:19], v[132:133]
	v_mov_b64_e32 v[20:21], v[134:135]
	v_pk_mul_f32 v[4:5], v[4:5], v[20:21]
	v_pk_mul_f32 v[2:3], v[2:3], v[18:19]
	v_pk_mul_f32 v[8:9], v[8:9], v[20:21]
	v_pk_mul_f32 v[6:7], v[6:7], v[18:19]
	v_pk_mul_f32 v[12:13], v[12:13], v[20:21]
	v_pk_mul_f32 v[10:11], v[10:11], v[18:19]
	v_pk_mul_f32 v[16:17], v[16:17], v[20:21]
	v_pk_mul_f32 v[14:15], v[14:15], v[18:19]
	v_cvt_pk_bf16_f32 v2, v2, v3
	v_cvt_pk_bf16_f32 v3, v4, v5
	v_cvt_pk_bf16_f32 v4, v6, v7
	v_cvt_pk_bf16_f32 v5, v8, v9
	v_cvt_pk_bf16_f32 v6, v10, v11
	v_cvt_pk_bf16_f32 v7, v12, v13
	v_cvt_pk_bf16_f32 v8, v14, v15
	v_cvt_pk_bf16_f32 v9, v16, v17
	global_store_dwordx2 v[80:81], v[2:3], off offset:1536
	global_store_dwordx2 v[58:59], v[4:5], off offset:512
	global_store_dwordx2 v[54:55], v[6:7], off offset:512
	global_store_dwordx2 v[50:51], v[8:9], off offset:512
	s_cbranch_scc1 .LBB0_58
